# cprep token-shift: 12 masked previous-token loads per block issued up front into dead registers, per-load vmcnt(0) replaced by counted waits (on top of scan rewrite)
# speedup vs baseline: 1.0252x; 1.0057x over previous
; #define LAS __attribute__((address_space(3)))
; __device__ __forceinline__ unsigned pk2(float lo, float hi) { const f32x2 v = {lo, hi}; const bf16x2_t b = __builtin_convertvector(v, bf16x2_t); return __builtin_bit_cast(unsigned, b); }
; __device__ __forceinline__ float ex2(float x) { return __builtin_amdgcn_exp2f(x); }
; __device__ __forceinline__ float rcpf_(float x) { return __builtin_amdgcn_rcpf(x); }
; __device__ __forceinline__ float sigmoidf_(float x) { return rcpf_(1.0f + ex2(-x * LOG2E)); }
; __device__ __forceinline__ void cprep_item(Frame& F, const Args& a, int l, int item, const bf16* P, unsigned char* ws) {
;     ...
;     LAS float* prm = (LAS float*)(F.lds + 20480);
;     if (tid < 128) { const int i0 = tid * 4;
;         const f32x4 p0 = *(const f32x4*)((const float*)a.in[20] + l * 512 + i0), p1 = *(const f32x4*)((const float*)a.in[22] + l * 512 + i0), p2 = *(const f32x4*)((const float*)a.in[25] + l * 512 + i0),
;                     p3 = *(const f32x4*)((const float*)a.in[26] + l * 512 + i0), p4 = *(const f32x4*)((const float*)a.in[27] + l * 512 + i0);
;         *(LAS f32x4*)(prm + i0) = p0; *(LAS f32x4*)(prm + 512 + i0) = p1; *(LAS f32x4*)(prm + 1024 + i0) = p2; *(LAS f32x4*)(prm + 1536 + i0) = p3; *(LAS f32x4*)(prm + 2048 + i0) = p4; }
;     {
;         const int r = tid >> 4, cg = tid & 15, row = row0 + r;
;         const bool first = samp ? ((r & 3) == 0) : ((row % SEQ) == 0);
;         const bf16* pc = P + (size_t)row * NPRE + PC0 + 1536 + cg * 16;
;         const float* ps = sh0 + (size_t)(r >> 2) * CSHIFT + 1536 + cg * 16;
;         unsigned o[8];
; #pragma unroll
;         for (int j = 0; j < 4; ++j) {
;             const f32x4 c = ldb4(pc + 4 * j); f32x4 p = first ? (samp ? *(const f32x4*)(ps + 4 * j) : (f32x4){0.f, 0.f, 0.f, 0.f}) : ldb4(pc - NPRE + 4 * j); const f32x4 m = *(const f32x4*)(mu + 1536 + cg * 16 + 4 * j);
;             f32x4 x = c + (p - c) * m;
; #pragma unroll
;             for (int e = 0; e < 4; ++e) { if (cg < 4) x[e] = 1.0f - 2.0f * rcpf_(1.0f + ex2(2.0f * LOG2E * x[e])); else if (cg >= 8) x[e] = sigmoidf_(x[e]); }
;             o[2 * j] = pk2(x[0], x[1]); o[2 * j + 1] = pk2(x[2], x[3]);
;         }
;         LAS u32x4* dst = (LAS u32x4*)(act + r * 264 + cg * 16);
;         dst[0] = (u32x4){o[0], o[1], o[2], o[3]}; dst[1] = (u32x4){o[4], o[5], o[6], o[7]};
;     }
;     LDS_WAIT(); __syncthreads();
.LBB0_623:
	s_or_b64 exec, exec, s[4:5]
	s_movk_i32 s4, 0x210
	v_cvt_pk_bf16_f32 v13, v2, v3
	v_mul_lo_u32 v2, v26, s4
	v_lshlrev_b32_e32 v3, 1, v27
	v_cvt_pk_bf16_f32 v16, v16, v17
	v_cvt_pk_bf16_f32 v17, v14, v15
	v_cvt_pk_bf16_f32 v14, v8, v9
	v_cvt_pk_bf16_f32 v15, v6, v7
	v_add3_u32 v2, 0, v2, v3
	v_cvt_pk_bf16_f32 v10, v22, v23
	v_cvt_pk_bf16_f32 v11, v20, v21
	v_cvt_pk_bf16_f32 v12, v4, v5
	ds_write_b128 v2, v[14:17]
	ds_write_b128 v2, v[10:13] offset:16
	v_or_b32_e32 v182, s20, v153
	v_mov_b64_e32 v[2:3], s[16:17]
	v_mad_i64_i32 v[2:3], s[4:5], v182, s68, v[2:3]
	v_ashrrev_i32_e32 v157, 31, v156
	v_lshl_add_u64 v[6:7], v[156:157], 1, v[2:3]
	v_add_co_u32_e32 v2, vcc, 0x1000, v6
	s_waitcnt lgkmcnt(0)
	s_waitcnt lgkmcnt(0)
	s_nop 0
	v_addc_co_u32_e32 v3, vcc, 0, v7, vcc
	s_barrier
	global_load_dwordx2 v[98:99], v[2:3], off offset:1024
	v_mov_b32_e32 v2, s20
	s_movk_i32 s4, 0xfef
	v_and_b32_e32 v224, 3, v155
	v_bitop3_b32 v2, v153, s4, v2 bitop3:0xc8
	s_movk_i32 s4, 0xea00
	v_cndmask_b32_e64 v2, v2, v224, s[0:1]
	s_mov_b32 s5, -1
	v_cmp_ne_u32_e64 s[42:43], 0, v2
	v_lshl_add_u64 v[22:23], v[6:7], 0, s[4:5]
	s_and_saveexec_b64 s[4:5], s[42:43]
	global_load_dwordx2 v[226:227], v[22:23], off
	global_load_dwordx2 v[228:229], v[22:23], off offset:1024
	global_load_dwordx2 v[230:231], v[22:23], off offset:2048
	global_load_dwordx2 v[232:233], v[22:23], off offset:32
	global_load_dwordx2 v[234:235], v[22:23], off offset:1056
	global_load_dwordx2 v[236:237], v[22:23], off offset:2080
	global_load_dwordx2 v[238:239], v[22:23], off offset:64
	global_load_dwordx2 v[240:241], v[22:23], off offset:1088
	global_load_dwordx2 v[242:243], v[22:23], off offset:2112
	global_load_dwordx2 v[244:245], v[22:23], off offset:96
	global_load_dwordx2 v[246:247], v[22:23], off offset:1120
	global_load_dwordx2 v[248:249], v[22:23], off offset:2144
	s_mov_b64 exec, s[4:5]
	s_and_saveexec_b64 s[4:5], s[42:43]
	s_xor_b64 s[4:5], exec, s[4:5]
	s_cbranch_execz .LBB0_625
	s_waitcnt vmcnt(11)
	v_lshlrev_b32_e32 v2, 16, v226
	v_and_b32_e32 v3, 0xffff0000, v226
	v_lshlrev_b32_e32 v4, 16, v227
	v_and_b32_e32 v5, 0xffff0000, v227

.LBB0_628:
	s_or_b64 exec, exec, s[4:5]
	s_mov_b64 s[4:5], 0x1400
	v_lshl_add_u64 v[160:161], v[156:157], 2, s[2:3]
	v_lshl_add_u64 v[106:107], v[6:7], 0, s[4:5]
	global_load_dwordx4 v[6:9], v[160:161], off
	global_load_dwordx2 v[100:101], v[106:107], off offset:1024
	s_and_saveexec_b64 s[2:3], s[42:43]
	s_xor_b64 s[2:3], exec, s[2:3]
	s_cbranch_execz .LBB0_630
	s_waitcnt vmcnt(12)
	v_lshlrev_b32_e32 v10, 16, v228
	v_and_b32_e32 v11, 0xffff0000, v228
	v_lshlrev_b32_e32 v12, 16, v229
	v_and_b32_e32 v13, 0xffff0000, v229

.LBB0_633:
	s_or_b64 exec, exec, s[2:3]
	global_load_dwordx4 v[14:17], v[160:161], off offset:2048
	global_load_dwordx2 v[102:103], v[106:107], off offset:2048
	s_and_saveexec_b64 s[2:3], s[42:43]
	s_xor_b64 s[2:3], exec, s[2:3]
	s_cbranch_execz .LBB0_635
	s_waitcnt vmcnt(13)
	v_lshlrev_b32_e32 v18, 16, v230
	v_and_b32_e32 v19, 0xffff0000, v230
	v_lshlrev_b32_e32 v20, 16, v231
	v_and_b32_e32 v21, 0xffff0000, v231

.LBB0_638:
	s_or_b64 exec, exec, s[2:3]
	v_add_co_u32_e32 v26, vcc, 0x1000, v160
	s_nop 1
	v_addc_co_u32_e32 v27, vcc, 0, v161, vcc
	global_load_dwordx4 v[26:29], v[26:27], off
	s_nop 0
	global_load_dwordx2 v[104:105], v[106:107], off offset:32
	s_and_saveexec_b64 s[2:3], s[42:43]
	s_xor_b64 s[2:3], exec, s[2:3]
	s_cbranch_execz .LBB0_640
	s_waitcnt vmcnt(14)
	v_lshlrev_b32_e32 v36, 16, v232
	v_and_b32_e32 v37, 0xffff0000, v232
	v_lshlrev_b32_e32 v38, 16, v233
	v_and_b32_e32 v39, 0xffff0000, v233

.LBB0_643:
	s_or_b64 exec, exec, s[2:3]
	global_load_dwordx4 v[40:43], v[160:161], off offset:64
	global_load_dwordx2 v[108:109], v[106:107], off offset:1056
	s_and_saveexec_b64 s[2:3], s[42:43]
	s_xor_b64 s[2:3], exec, s[2:3]
	s_cbranch_execz .LBB0_645
	s_waitcnt vmcnt(15)
	v_lshlrev_b32_e32 v52, 16, v234
	v_and_b32_e32 v53, 0xffff0000, v234
	v_lshlrev_b32_e32 v54, 16, v235
	v_and_b32_e32 v55, 0xffff0000, v235

.LBB0_648:
	s_or_b64 exec, exec, s[2:3]
	global_load_dwordx4 v[56:59], v[160:161], off offset:2112
	global_load_dwordx2 v[110:111], v[106:107], off offset:2080
	s_and_saveexec_b64 s[2:3], s[42:43]
	s_xor_b64 s[2:3], exec, s[2:3]
	s_cbranch_execz .LBB0_650
	s_waitcnt vmcnt(16)
	v_lshlrev_b32_e32 v60, 16, v236
	v_and_b32_e32 v61, 0xffff0000, v236
	v_lshlrev_b32_e32 v62, 16, v237
	v_and_b32_e32 v63, 0xffff0000, v237

.LBB0_653:
	s_or_b64 exec, exec, s[2:3]
	v_lshl_add_u64 v[184:185], v[160:161], 0, 64
	v_add_co_u32_e32 v30, vcc, 0x1000, v184
	s_nop 1
	v_addc_co_u32_e32 v31, vcc, 0, v185, vcc
	global_load_dwordx4 v[64:67], v[30:31], off
	global_load_dwordx2 v[112:113], v[106:107], off offset:64
	s_and_saveexec_b64 s[2:3], s[42:43]
	s_xor_b64 s[2:3], exec, s[2:3]
	s_cbranch_execz .LBB0_655
	s_waitcnt vmcnt(17)
	v_lshlrev_b32_e32 v48, 16, v238
	v_and_b32_e32 v49, 0xffff0000, v238
	v_lshlrev_b32_e32 v50, 16, v239
	v_and_b32_e32 v51, 0xffff0000, v239

.LBB0_658:
	s_or_b64 exec, exec, s[2:3]
	global_load_dwordx4 v[68:71], v[160:161], off offset:128
	global_load_dwordx2 v[114:115], v[106:107], off offset:1088
	s_and_saveexec_b64 s[2:3], s[42:43]
	s_xor_b64 s[2:3], exec, s[2:3]
	s_cbranch_execz .LBB0_660
	s_waitcnt vmcnt(18)
	v_lshlrev_b32_e32 v72, 16, v240
	v_and_b32_e32 v73, 0xffff0000, v240
	v_lshlrev_b32_e32 v74, 16, v241
	v_and_b32_e32 v75, 0xffff0000, v241

.LBB0_663:
	s_or_b64 exec, exec, s[2:3]
	global_load_dwordx4 v[76:79], v[160:161], off offset:2176
	global_load_dwordx2 v[116:117], v[106:107], off offset:2112
	s_and_saveexec_b64 s[2:3], s[42:43]
	s_xor_b64 s[2:3], exec, s[2:3]
	s_cbranch_execz .LBB0_665
	s_waitcnt vmcnt(19)
	v_lshlrev_b32_e32 v44, 16, v242
	v_and_b32_e32 v45, 0xffff0000, v242
	v_lshlrev_b32_e32 v46, 16, v243
	v_and_b32_e32 v47, 0xffff0000, v243

.LBB0_668:
	s_or_b64 exec, exec, s[2:3]
	v_lshl_add_u64 v[186:187], v[160:161], 0, s[22:23]
	v_add_co_u32_e32 v30, vcc, 0x1000, v186
	s_nop 1
	v_addc_co_u32_e32 v31, vcc, 0, v187, vcc
	global_load_dwordx4 v[80:83], v[30:31], off
	global_load_dwordx2 v[118:119], v[106:107], off offset:96
	s_and_saveexec_b64 s[2:3], s[42:43]
	s_xor_b64 s[2:3], exec, s[2:3]
	s_cbranch_execz .LBB0_670
	s_waitcnt vmcnt(20)
	v_lshlrev_b32_e32 v30, 16, v244
	v_and_b32_e32 v31, 0xffff0000, v244
	v_lshlrev_b32_e32 v32, 16, v245
	v_and_b32_e32 v33, 0xffff0000, v245

.LBB0_673:
	s_or_b64 exec, exec, s[2:3]
	global_load_dwordx4 v[84:87], v[160:161], off offset:192
	global_load_dwordx2 v[120:121], v[106:107], off offset:1120
	s_and_saveexec_b64 s[2:3], s[42:43]
	s_xor_b64 s[2:3], exec, s[2:3]
	s_cbranch_execz .LBB0_675
	s_waitcnt vmcnt(21)
	v_lshlrev_b32_e32 v88, 16, v246
	v_and_b32_e32 v89, 0xffff0000, v246
	v_lshlrev_b32_e32 v90, 16, v247
	v_and_b32_e32 v91, 0xffff0000, v247

.LBB0_678:
	s_or_b64 exec, exec, s[2:3]
	global_load_dwordx4 v[92:95], v[160:161], off offset:2240
	s_nop 0
	global_load_dwordx2 v[106:107], v[106:107], off offset:2144
	s_and_saveexec_b64 s[2:3], s[42:43]
	s_xor_b64 s[2:3], exec, s[2:3]
	s_cbranch_execz .LBB0_680
	s_waitcnt vmcnt(22)
	v_lshlrev_b32_e32 v22, 16, v248
	v_and_b32_e32 v23, 0xffff0000, v248
	v_lshlrev_b32_e32 v24, 16, v249
	v_and_b32_e32 v25, 0xffff0000, v249

.LBB0_685:
	s_or_b64 exec, exec, s[2:3]
	v_or_b32_e32 v34, 16, v153
	v_or_b32_e32 v144, s20, v34
	s_waitcnt lgkmcnt(0)
	v_mov_b64_e32 v[30:31], s[16:17]
	v_mad_i64_i32 v[30:31], s[2:3], v144, s68, v[30:31]
	v_lshlrev_b64 v[32:33], 1, v[156:157]
	v_lshl_add_u64 v[48:49], v[30:31], 0, v[32:33]
	v_add_co_u32_e32 v44, vcc, 0x1000, v48
	s_movk_i32 s2, 0xea00
	s_nop 0
	v_addc_co_u32_e32 v45, vcc, 0, v49, vcc
	global_load_dwordx2 v[146:147], v[44:45], off offset:1024
	s_mov_b32 s3, -1
	v_cmp_ne_u32_e32 vcc, 0, v224
	s_xor_b64 s[0:1], s[0:1], -1
	v_lshl_add_u64 v[30:31], v[30:31], 0, s[2:3]
	s_or_b64 s[0:1], s[0:1], vcc
	v_lshl_add_u64 v[32:33], v[30:31], 0, v[32:33]
	s_and_saveexec_b64 s[2:3], s[0:1]
	global_load_dwordx2 v[226:227], v[32:33], off
	global_load_dwordx2 v[228:229], v[32:33], off offset:1024
	global_load_dwordx2 v[230:231], v[32:33], off offset:2048
	global_load_dwordx2 v[232:233], v[32:33], off offset:32
	global_load_dwordx2 v[234:235], v[32:33], off offset:1056
	global_load_dwordx2 v[236:237], v[32:33], off offset:2080
	global_load_dwordx2 v[238:239], v[32:33], off offset:64
	global_load_dwordx2 v[240:241], v[32:33], off offset:1088
	global_load_dwordx2 v[242:243], v[32:33], off offset:2112
	global_load_dwordx2 v[244:245], v[32:33], off offset:96
	global_load_dwordx2 v[246:247], v[32:33], off offset:1120
	global_load_dwordx2 v[248:249], v[32:33], off offset:2144
	s_mov_b64 exec, s[2:3]
	s_and_saveexec_b64 s[2:3], s[0:1]
	s_xor_b64 s[2:3], exec, s[2:3]
	s_cbranch_execz .LBB0_687
	s_waitcnt vmcnt(11)
	v_lshlrev_b32_e32 v44, 16, v226
	v_and_b32_e32 v45, 0xffff0000, v226
	v_lshlrev_b32_e32 v46, 16, v227
	v_and_b32_e32 v47, 0xffff0000, v227

.LBB0_689:
	s_or_b64 exec, exec, s[2:3]
	s_mov_b64 s[2:3], 0x1400
	v_lshl_add_u64 v[116:117], v[48:49], 0, s[2:3]
	global_load_dwordx4 v[60:63], v[160:161], off
	global_load_dwordx2 v[148:149], v[116:117], off offset:1024
	s_and_saveexec_b64 s[2:3], s[0:1]
	s_xor_b64 s[2:3], exec, s[2:3]
	s_cbranch_execz .LBB0_691
	s_waitcnt vmcnt(12)
	v_lshlrev_b32_e32 v68, 16, v228
	v_and_b32_e32 v69, 0xffff0000, v228
	v_lshlrev_b32_e32 v70, 16, v229
	v_and_b32_e32 v71, 0xffff0000, v229

.LBB0_693:
	s_or_b64 exec, exec, s[2:3]
	global_load_dwordx4 v[72:75], v[160:161], off offset:2048
	global_load_dwordx2 v[150:151], v[116:117], off offset:2048
	s_and_saveexec_b64 s[2:3], s[0:1]
	s_xor_b64 s[2:3], exec, s[2:3]
	s_cbranch_execz .LBB0_695
	s_waitcnt vmcnt(13)
	v_lshlrev_b32_e32 v76, 16, v230
	v_and_b32_e32 v77, 0xffff0000, v230
	v_lshlrev_b32_e32 v78, 16, v231
	v_and_b32_e32 v79, 0xffff0000, v231

.LBB0_697:
	s_or_b64 exec, exec, s[2:3]
	s_mov_b64 s[2:3], 0x1000
	v_lshl_add_u64 v[32:33], v[160:161], 0, s[2:3]
	global_load_dwordx4 v[80:83], v[32:33], off
	global_load_dwordx2 v[182:183], v[116:117], off offset:32
	v_lshl_add_u64 v[32:33], v[180:181], 1, v[30:31]
	s_and_saveexec_b64 s[2:3], s[0:1]
	s_xor_b64 s[2:3], exec, s[2:3]
	s_cbranch_execz .LBB0_699
	s_waitcnt vmcnt(14)
	v_lshlrev_b32_e32 v84, 16, v232
	v_and_b32_e32 v85, 0xffff0000, v232
	v_lshlrev_b32_e32 v86, 16, v233
	v_and_b32_e32 v87, 0xffff0000, v233

.LBB0_701:
	s_or_b64 exec, exec, s[2:3]
	global_load_dwordx4 v[88:91], v[184:185], off
	global_load_dwordx2 v[190:191], v[116:117], off offset:1056
	s_and_saveexec_b64 s[2:3], s[0:1]
	s_xor_b64 s[2:3], exec, s[2:3]
	s_cbranch_execz .LBB0_703
	s_waitcnt vmcnt(15)
	v_lshlrev_b32_e32 v92, 16, v234
	v_and_b32_e32 v93, 0xffff0000, v234
	v_lshlrev_b32_e32 v94, 16, v235
	v_and_b32_e32 v95, 0xffff0000, v235

.LBB0_705:
	s_or_b64 exec, exec, s[2:3]
	global_load_dwordx4 v[100:103], v[160:161], off offset:2112
	global_load_dwordx2 v[192:193], v[116:117], off offset:2080
	s_and_saveexec_b64 s[2:3], s[0:1]
	s_xor_b64 s[2:3], exec, s[2:3]
	s_cbranch_execz .LBB0_707
	s_waitcnt vmcnt(16)
	v_lshlrev_b32_e32 v104, 16, v236
	v_and_b32_e32 v105, 0xffff0000, v236
	v_lshlrev_b32_e32 v106, 16, v237
	v_and_b32_e32 v107, 0xffff0000, v237

.LBB0_709:
	s_or_b64 exec, exec, s[2:3]
	s_mov_b64 s[2:3], 0x1000
	v_lshl_add_u64 v[32:33], v[184:185], 0, s[2:3]
	global_load_dwordx4 v[108:111], v[32:33], off
	global_load_dwordx2 v[184:185], v[116:117], off offset:64
	v_lshl_add_u64 v[32:33], v[162:163], 1, v[30:31]
	s_and_saveexec_b64 s[2:3], s[0:1]
	s_xor_b64 s[2:3], exec, s[2:3]
	s_cbranch_execz .LBB0_711
	s_waitcnt vmcnt(17)
	v_lshlrev_b32_e32 v96, 16, v238
	v_and_b32_e32 v97, 0xffff0000, v238
	v_lshlrev_b32_e32 v98, 16, v239
	v_and_b32_e32 v99, 0xffff0000, v239

.LBB0_713:
	s_or_b64 exec, exec, s[2:3]
	global_load_dwordx4 v[112:115], v[186:187], off
	global_load_dwordx2 v[194:195], v[116:117], off offset:1088
	s_and_saveexec_b64 s[2:3], s[0:1]
	s_xor_b64 s[2:3], exec, s[2:3]
	s_cbranch_execz .LBB0_715
	s_waitcnt vmcnt(18)
	v_lshlrev_b32_e32 v120, 16, v240
	v_and_b32_e32 v121, 0xffff0000, v240
	v_lshlrev_b32_e32 v122, 16, v241
	v_and_b32_e32 v123, 0xffff0000, v241

.LBB0_717:
	s_or_b64 exec, exec, s[2:3]
	global_load_dwordx4 v[124:127], v[160:161], off offset:2176
	global_load_dwordx2 v[196:197], v[116:117], off offset:2112
	s_and_saveexec_b64 s[2:3], s[0:1]
	s_xor_b64 s[2:3], exec, s[2:3]
	s_cbranch_execz .LBB0_719
	s_waitcnt vmcnt(19)
	v_lshlrev_b32_e32 v48, 16, v242
	v_and_b32_e32 v49, 0xffff0000, v242
	v_lshlrev_b32_e32 v50, 16, v243
	v_and_b32_e32 v51, 0xffff0000, v243

.LBB0_721:
	s_or_b64 exec, exec, s[2:3]
	s_mov_b64 s[2:3], 0x1000
	v_lshl_add_u64 v[32:33], v[186:187], 0, s[2:3]
	global_load_dwordx4 v[128:131], v[32:33], off
	global_load_dwordx2 v[186:187], v[116:117], off offset:96
	v_lshl_add_u64 v[200:201], v[158:159], 1, v[30:31]
	s_and_saveexec_b64 s[2:3], s[0:1]
	s_xor_b64 s[2:3], exec, s[2:3]
	s_cbranch_execz .LBB0_723
	s_waitcnt vmcnt(20)
	v_lshlrev_b32_e32 v30, 16, v244
	v_and_b32_e32 v31, 0xffff0000, v244
	v_lshlrev_b32_e32 v32, 16, v245
	v_and_b32_e32 v33, 0xffff0000, v245

.LBB0_725:
	s_or_b64 exec, exec, s[2:3]
	global_load_dwordx4 v[132:135], v[188:189], off
	global_load_dwordx2 v[198:199], v[116:117], off offset:1120
	s_and_saveexec_b64 s[2:3], s[0:1]
	s_xor_b64 s[2:3], exec, s[2:3]
	s_cbranch_execz .LBB0_727
	s_waitcnt vmcnt(21)
	v_lshlrev_b32_e32 v136, 16, v246
	v_and_b32_e32 v137, 0xffff0000, v246
	v_lshlrev_b32_e32 v138, 16, v247
	v_and_b32_e32 v139, 0xffff0000, v247

.LBB0_729:
	s_or_b64 exec, exec, s[2:3]
	global_load_dwordx4 v[140:143], v[160:161], off offset:2240
	s_nop 0
	global_load_dwordx2 v[160:161], v[116:117], off offset:2144
	s_and_saveexec_b64 s[2:3], s[0:1]
	s_xor_b64 s[0:1], exec, s[2:3]
	s_cbranch_execz .LBB0_731
	s_waitcnt vmcnt(22)
	v_lshlrev_b32_e32 v116, 16, v248
	v_and_b32_e32 v117, 0xffff0000, v248
	v_lshlrev_b32_e32 v118, 16, v249
	v_and_b32_e32 v119, 0xffff0000, v249
